# K|Q|Z|V projection GEMM: column tile index xor 4 on odd row groups so every workgroup gets two z-gate (silu epilogue) tiles instead of four or none
# speedup vs baseline: 1.0007x; 1.0007x over previous
.LBB0_652:
	s_ashr_i32 s5, s5, 3
	s_add_i32 s5, s25, s5
	s_ashr_i32 s22, s5, 31
	s_lshr_b32 s22, s22, 26
	s_add_i32 s22, s5, s22
	s_ashr_i32 s23, s22, 6
	s_lshl_b32 s23, s23, 2
	s_sub_i32 s24, 0x80, s23
	s_min_i32 s24, s24, 4
	s_abs_i32 s25, s24
	v_cvt_f32_u32_e32 v0, s25
	s_sub_i32 s27, 0, s25
	s_andn2_b32 s22, s22, 63
	s_sub_i32 s5, s5, s22
	v_rcp_iflag_f32_e32 v0, v0
	s_abs_i32 s22, s5
	s_xor_b32 s26, s5, s24
	s_ashr_i32 s26, s26, 31
	v_mul_f32_e32 v0, 0x4f7ffffe, v0
	v_cvt_u32_f32_e32 v0, v0
	s_nop 0
	v_readfirstlane_b32 s28, v0
	s_mul_i32 s27, s27, s28
	s_mul_hi_u32 s27, s28, s27
	s_add_i32 s28, s28, s27
	s_mul_hi_u32 s27, s22, s28
	s_mul_i32 s28, s27, s25
	s_sub_i32 s22, s22, s28
	s_add_i32 s29, s27, 1
	s_sub_i32 s28, s22, s25
	s_cmp_ge_u32 s22, s25
	s_cselect_b32 s27, s29, s27
	s_cselect_b32 s22, s28, s22
	s_add_i32 s28, s27, 1
	s_cmp_ge_u32 s22, s25
	s_cselect_b32 s22, s28, s27
	s_xor_b32 s22, s22, s26
	s_sub_i32 s22, s22, s26
	s_mul_i32 s24, s22, s24
	s_sub_i32 s5, s5, s24
	s_add_i32 s24, s23, s5
	s_and_b32 s26, s23, 4
	s_xor_b32 s22, s22, s26
